# OutB and Final GEMM epilogues: touch-prefetch of the tile's gate / accumulate / residual operands at epilogue start
# baseline (speedup 1.0000x reference)
.LBB0_654:
	v_lshl_add_u32 v144, s40, 8, v146
	v_lshl_or_b32 v142, s39, 8, v148
	v_ashrrev_i32_e32 v145, 31, v144
	v_ashrrev_i32_e32 v143, 31, v142
	v_lshlrev_b64 v[140:141], 10, v[144:145]
	v_lshl_add_u64 v[140:141], v[140:141], 0, v[142:143]
	v_lshlrev_b64 v[140:141], 1, v[140:141]
	s_mov_b32 s98, s10
	s_mov_b32 s99, s11
	global_load_dwordx4 v[178:181], v140, s[98:99]
	global_load_dwordx4 v[182:185], v140, s[98:99] offset:256
	s_mov_b32 s98, s8
	s_mov_b32 s99, s9
	global_load_dwordx4 v[186:189], v140, s[98:99]
	global_load_dwordx4 v[190:193], v140, s[98:99] offset:256
	s_add_u32 s98, s10, 0x8000
	s_addc_u32 s99, s11, 0
	global_load_dwordx4 v[208:211], v140, s[98:99]
	global_load_dwordx4 v[212:215], v140, s[98:99] offset:256
	s_add_u32 s98, s8, 0x8000
	s_addc_u32 s99, s9, 0
	global_load_dwordx4 v[216:219], v140, s[98:99]
	global_load_dwordx4 v[220:223], v140, s[98:99] offset:256
	s_add_u32 s98, s10, 0x10000
	s_addc_u32 s99, s11, 0
	global_load_dwordx4 v[178:181], v140, s[98:99]
	global_load_dwordx4 v[182:185], v140, s[98:99] offset:256
	s_add_u32 s98, s8, 0x10000
	s_addc_u32 s99, s9, 0
	global_load_dwordx4 v[186:189], v140, s[98:99]
	global_load_dwordx4 v[190:193], v140, s[98:99] offset:256
	s_add_u32 s98, s10, 0x18000
	s_addc_u32 s99, s11, 0
	global_load_dwordx4 v[208:211], v140, s[98:99]
	global_load_dwordx4 v[212:215], v140, s[98:99] offset:256
	s_add_u32 s98, s8, 0x18000
	s_addc_u32 s99, s9, 0
	global_load_dwordx4 v[216:219], v140, s[98:99]
	global_load_dwordx4 v[220:223], v140, s[98:99] offset:256
	s_add_u32 s98, s10, 0x40000
	s_addc_u32 s99, s11, 0
	global_load_dwordx4 v[178:181], v140, s[98:99]
	global_load_dwordx4 v[182:185], v140, s[98:99] offset:256
	s_add_u32 s98, s8, 0x40000
	s_addc_u32 s99, s9, 0
	global_load_dwordx4 v[186:189], v140, s[98:99]
	global_load_dwordx4 v[190:193], v140, s[98:99] offset:256
	s_add_u32 s98, s10, 0x48000
	s_addc_u32 s99, s11, 0
	global_load_dwordx4 v[208:211], v140, s[98:99]
	global_load_dwordx4 v[212:215], v140, s[98:99] offset:256
	s_add_u32 s98, s8, 0x48000
	s_addc_u32 s99, s9, 0
	global_load_dwordx4 v[216:219], v140, s[98:99]
	global_load_dwordx4 v[220:223], v140, s[98:99] offset:256
	s_add_u32 s98, s10, 0x50000
	s_addc_u32 s99, s11, 0
	global_load_dwordx4 v[178:181], v140, s[98:99]
	global_load_dwordx4 v[182:185], v140, s[98:99] offset:256
	s_add_u32 s98, s8, 0x50000
	s_addc_u32 s99, s9, 0
	global_load_dwordx4 v[186:189], v140, s[98:99]
	global_load_dwordx4 v[190:193], v140, s[98:99] offset:256
	s_add_u32 s98, s10, 0x58000
	s_addc_u32 s99, s11, 0
	global_load_dwordx4 v[208:211], v140, s[98:99]
	global_load_dwordx4 v[212:215], v140, s[98:99] offset:256
	s_add_u32 s98, s8, 0x58000
	s_addc_u32 s99, s9, 0
	global_load_dwordx4 v[216:219], v140, s[98:99]
	global_load_dwordx4 v[220:223], v140, s[98:99] offset:256
	v_lshl_add_u64 v[154:155], s[10:11], 0, v[140:141]
	global_load_dwordx4 v[150:153], v[154:155], off
	v_lshl_add_u64 v[164:165], s[8:9], 0, v[140:141]
	s_mov_b64 s[2:3], 0x40000
	s_andn2_b64 vcc, exec, s[6:7]
	s_waitcnt vmcnt(0)
	v_lshlrev_b32_e32 v156, 16, v150
	v_and_b32_e32 v157, 0xffff0000, v150
	v_lshlrev_b32_e32 v158, 16, v151
	v_and_b32_e32 v159, 0xffff0000, v151
	v_lshlrev_b32_e32 v160, 16, v152
	v_and_b32_e32 v161, 0xffff0000, v152
	v_lshlrev_b32_e32 v162, 16, v153
	v_and_b32_e32 v163, 0xffff0000, v153
	global_load_dwordx4 v[150:153], v[164:165], off
	s_waitcnt vmcnt(0)
	v_lshlrev_b32_e32 v166, 16, v150
	v_and_b32_e32 v167, 0xffff0000, v150
	v_lshlrev_b32_e32 v150, 16, v151
	v_and_b32_e32 v151, 0xffff0000, v151
	v_lshlrev_b32_e32 v168, 16, v152
	v_and_b32_e32 v169, 0xffff0000, v152
	v_lshlrev_b32_e32 v152, 16, v153
	v_and_b32_e32 v153, 0xffff0000, v153
	v_pk_fma_f32 v[126:127], v[126:127], v[158:159], v[150:151]
	v_pk_fma_f32 v[124:125], v[124:125], v[156:157], v[166:167]
	v_pk_fma_f32 v[150:151], v[122:123], v[162:163], v[152:153]
	v_pk_fma_f32 v[122:123], v[120:121], v[160:161], v[168:169]
	v_cvt_pk_bf16_f32 v120, v124, v125
	v_cvt_pk_bf16_f32 v121, v126, v127
	v_cvt_pk_bf16_f32 v122, v122, v123
	v_cvt_pk_bf16_f32 v123, v150, v151
	global_store_dwordx4 v[164:165], v[120:123], off
	global_load_dwordx4 v[120:123], v[154:155], off offset:256
	s_waitcnt vmcnt(0)
	v_lshlrev_b32_e32 v124, 16, v120
	v_and_b32_e32 v125, 0xffff0000, v120
	v_lshlrev_b32_e32 v126, 16, v121
	v_and_b32_e32 v127, 0xffff0000, v121
	v_lshlrev_b32_e32 v150, 16, v122
	v_and_b32_e32 v151, 0xffff0000, v122
	v_lshlrev_b32_e32 v152, 16, v123
	v_and_b32_e32 v153, 0xffff0000, v123
	global_load_dwordx4 v[120:123], v[164:165], off offset:256
	s_waitcnt vmcnt(0)
	v_lshlrev_b32_e32 v154, 16, v120
	v_and_b32_e32 v155, 0xffff0000, v120
	v_lshlrev_b32_e32 v120, 16, v121
	v_and_b32_e32 v121, 0xffff0000, v121
	v_lshlrev_b32_e32 v156, 16, v122
	v_and_b32_e32 v157, 0xffff0000, v122
	v_lshlrev_b32_e32 v122, 16, v123
	v_and_b32_e32 v123, 0xffff0000, v123
	v_pk_fma_f32 v[118:119], v[118:119], v[126:127], v[120:121]
	v_pk_fma_f32 v[116:117], v[116:117], v[124:125], v[154:155]
	v_pk_fma_f32 v[120:121], v[114:115], v[152:153], v[122:123]
	v_pk_fma_f32 v[114:115], v[112:113], v[150:151], v[156:157]
	v_cvt_pk_bf16_f32 v112, v116, v117
	v_cvt_pk_bf16_f32 v113, v118, v119
	v_cvt_pk_bf16_f32 v114, v114, v115
	v_cvt_pk_bf16_f32 v115, v120, v121
	global_store_dwordx4 v[164:165], v[112:115], off offset:256
	s_nop 1
	v_or_b32_e32 v112, 16, v144
	v_ashrrev_i32_e32 v113, 31, v112
	v_lshlrev_b64 v[112:113], 10, v[112:113]
	v_lshl_add_u64 v[112:113], v[112:113], 0, v[142:143]
	v_lshlrev_b64 v[118:119], 1, v[112:113]
	v_lshl_add_u64 v[112:113], s[10:11], 0, v[118:119]
	global_load_dwordx4 v[114:117], v[112:113], off
	v_lshl_add_u64 v[118:119], s[8:9], 0, v[118:119]
	s_waitcnt vmcnt(0)
	v_lshlrev_b32_e32 v120, 16, v114
	v_and_b32_e32 v121, 0xffff0000, v114
	v_lshlrev_b32_e32 v122, 16, v115
	v_and_b32_e32 v123, 0xffff0000, v115
	v_lshlrev_b32_e32 v124, 16, v116
	v_and_b32_e32 v125, 0xffff0000, v116
	v_lshlrev_b32_e32 v126, 16, v117
	v_and_b32_e32 v127, 0xffff0000, v117
	global_load_dwordx4 v[114:117], v[118:119], off
	s_waitcnt vmcnt(0)
	v_lshlrev_b32_e32 v150, 16, v114
	v_and_b32_e32 v151, 0xffff0000, v114
	v_lshlrev_b32_e32 v114, 16, v115
	v_and_b32_e32 v115, 0xffff0000, v115
	v_lshlrev_b32_e32 v152, 16, v116
	v_and_b32_e32 v153, 0xffff0000, v116
	v_lshlrev_b32_e32 v116, 16, v117
	v_and_b32_e32 v117, 0xffff0000, v117
	v_pk_fma_f32 v[110:111], v[110:111], v[122:123], v[114:115]
	v_pk_fma_f32 v[108:109], v[108:109], v[120:121], v[150:151]
	v_pk_fma_f32 v[114:115], v[106:107], v[126:127], v[116:117]
	v_pk_fma_f32 v[106:107], v[104:105], v[124:125], v[152:153]
	v_cvt_pk_bf16_f32 v104, v108, v109
	v_cvt_pk_bf16_f32 v105, v110, v111
	v_cvt_pk_bf16_f32 v106, v106, v107
	v_cvt_pk_bf16_f32 v107, v114, v115
	global_store_dwordx4 v[118:119], v[104:107], off
	global_load_dwordx4 v[104:107], v[112:113], off offset:256
	s_waitcnt vmcnt(0)
	v_lshlrev_b32_e32 v108, 16, v104
	v_and_b32_e32 v109, 0xffff0000, v104
	v_lshlrev_b32_e32 v110, 16, v105
	v_and_b32_e32 v111, 0xffff0000, v105
	v_lshlrev_b32_e32 v112, 16, v106
	v_and_b32_e32 v113, 0xffff0000, v106
	v_lshlrev_b32_e32 v114, 16, v107
	v_and_b32_e32 v115, 0xffff0000, v107
	global_load_dwordx4 v[104:107], v[118:119], off offset:256
	s_waitcnt vmcnt(0)
	v_lshlrev_b32_e32 v116, 16, v104
	v_and_b32_e32 v117, 0xffff0000, v104
	v_lshlrev_b32_e32 v104, 16, v105
	v_and_b32_e32 v105, 0xffff0000, v105
	v_lshlrev_b32_e32 v120, 16, v106
	v_and_b32_e32 v121, 0xffff0000, v106
	v_lshlrev_b32_e32 v106, 16, v107
	v_and_b32_e32 v107, 0xffff0000, v107
	v_pk_fma_f32 v[102:103], v[102:103], v[110:111], v[104:105]
	v_pk_fma_f32 v[100:101], v[100:101], v[108:109], v[116:117]
	v_pk_fma_f32 v[104:105], v[98:99], v[114:115], v[106:107]
	v_pk_fma_f32 v[98:99], v[96:97], v[112:113], v[120:121]
	v_cvt_pk_bf16_f32 v96, v100, v101
	v_cvt_pk_bf16_f32 v97, v102, v103
	v_cvt_pk_bf16_f32 v98, v98, v99
	v_cvt_pk_bf16_f32 v99, v104, v105
	global_store_dwordx4 v[118:119], v[96:99], off offset:256
	s_nop 1
	v_or_b32_e32 v96, 32, v144
	v_ashrrev_i32_e32 v97, 31, v96
	v_lshlrev_b64 v[96:97], 10, v[96:97]
	v_lshl_add_u64 v[96:97], v[96:97], 0, v[142:143]
	v_lshlrev_b64 v[102:103], 1, v[96:97]
	v_lshl_add_u64 v[96:97], s[10:11], 0, v[102:103]
	global_load_dwordx4 v[98:101], v[96:97], off
	v_lshl_add_u64 v[102:103], s[8:9], 0, v[102:103]
	s_waitcnt vmcnt(0)
	v_lshlrev_b32_e32 v104, 16, v98
	v_and_b32_e32 v105, 0xffff0000, v98
	v_lshlrev_b32_e32 v106, 16, v99
	v_and_b32_e32 v107, 0xffff0000, v99
	v_lshlrev_b32_e32 v108, 16, v100
	v_and_b32_e32 v109, 0xffff0000, v100
	v_lshlrev_b32_e32 v110, 16, v101
	v_and_b32_e32 v111, 0xffff0000, v101
	global_load_dwordx4 v[98:101], v[102:103], off
	s_waitcnt vmcnt(0)
	v_lshlrev_b32_e32 v112, 16, v98
	v_and_b32_e32 v113, 0xffff0000, v98
	v_lshlrev_b32_e32 v98, 16, v99
	v_and_b32_e32 v99, 0xffff0000, v99
	v_lshlrev_b32_e32 v114, 16, v100
	v_and_b32_e32 v115, 0xffff0000, v100
	v_lshlrev_b32_e32 v100, 16, v101
	v_and_b32_e32 v101, 0xffff0000, v101
	v_pk_fma_f32 v[94:95], v[94:95], v[106:107], v[98:99]
	v_pk_fma_f32 v[92:93], v[92:93], v[104:105], v[112:113]
	v_pk_fma_f32 v[98:99], v[90:91], v[110:111], v[100:101]
	v_pk_fma_f32 v[90:91], v[88:89], v[108:109], v[114:115]
	v_cvt_pk_bf16_f32 v88, v92, v93
	v_cvt_pk_bf16_f32 v89, v94, v95
	v_cvt_pk_bf16_f32 v90, v90, v91
	v_cvt_pk_bf16_f32 v91, v98, v99
	global_store_dwordx4 v[102:103], v[88:91], off
	global_load_dwordx4 v[88:91], v[96:97], off offset:256
	s_waitcnt vmcnt(0)
	v_lshlrev_b32_e32 v92, 16, v88
	v_and_b32_e32 v93, 0xffff0000, v88
	v_lshlrev_b32_e32 v94, 16, v89
	v_and_b32_e32 v95, 0xffff0000, v89
	v_lshlrev_b32_e32 v96, 16, v90
	v_and_b32_e32 v97, 0xffff0000, v90
	v_lshlrev_b32_e32 v98, 16, v91
	v_and_b32_e32 v99, 0xffff0000, v91
	global_load_dwordx4 v[88:91], v[102:103], off offset:256
	s_waitcnt vmcnt(0)
	v_lshlrev_b32_e32 v100, 16, v88
	v_and_b32_e32 v101, 0xffff0000, v88
	v_lshlrev_b32_e32 v88, 16, v89
	v_and_b32_e32 v89, 0xffff0000, v89
	v_lshlrev_b32_e32 v104, 16, v90
	v_and_b32_e32 v105, 0xffff0000, v90
	v_lshlrev_b32_e32 v90, 16, v91
	v_and_b32_e32 v91, 0xffff0000, v91
	v_pk_fma_f32 v[86:87], v[86:87], v[94:95], v[88:89]
	v_pk_fma_f32 v[84:85], v[84:85], v[92:93], v[100:101]
	v_pk_fma_f32 v[88:89], v[82:83], v[98:99], v[90:91]
	v_pk_fma_f32 v[82:83], v[80:81], v[96:97], v[104:105]
	v_cvt_pk_bf16_f32 v80, v84, v85
	v_cvt_pk_bf16_f32 v81, v86, v87
	v_cvt_pk_bf16_f32 v82, v82, v83
	v_cvt_pk_bf16_f32 v83, v88, v89
	global_store_dwordx4 v[102:103], v[80:83], off offset:256
	s_nop 1
	v_or_b32_e32 v80, 48, v144
	v_ashrrev_i32_e32 v81, 31, v80
	v_lshlrev_b64 v[80:81], 10, v[80:81]
	v_lshl_add_u64 v[80:81], v[80:81], 0, v[142:143]
	v_lshlrev_b64 v[86:87], 1, v[80:81]
	v_lshl_add_u64 v[80:81], s[10:11], 0, v[86:87]
	global_load_dwordx4 v[82:85], v[80:81], off
	v_lshl_add_u64 v[86:87], s[8:9], 0, v[86:87]
	s_waitcnt vmcnt(0)
	v_lshlrev_b32_e32 v88, 16, v82
	v_and_b32_e32 v89, 0xffff0000, v82
	v_lshlrev_b32_e32 v90, 16, v83
	v_and_b32_e32 v91, 0xffff0000, v83
	v_lshlrev_b32_e32 v92, 16, v84
	v_and_b32_e32 v93, 0xffff0000, v84
	v_lshlrev_b32_e32 v94, 16, v85
	v_and_b32_e32 v95, 0xffff0000, v85
	global_load_dwordx4 v[82:85], v[86:87], off
	s_waitcnt vmcnt(0)
	v_lshlrev_b32_e32 v96, 16, v82
	v_and_b32_e32 v97, 0xffff0000, v82
	v_lshlrev_b32_e32 v82, 16, v83
	v_and_b32_e32 v83, 0xffff0000, v83
	v_lshlrev_b32_e32 v98, 16, v84
	v_and_b32_e32 v99, 0xffff0000, v84
	v_lshlrev_b32_e32 v84, 16, v85
	v_and_b32_e32 v85, 0xffff0000, v85
	v_pk_fma_f32 v[78:79], v[78:79], v[90:91], v[82:83]
	v_pk_fma_f32 v[76:77], v[76:77], v[88:89], v[96:97]
	v_pk_fma_f32 v[82:83], v[74:75], v[94:95], v[84:85]
	v_pk_fma_f32 v[74:75], v[72:73], v[92:93], v[98:99]
	v_cvt_pk_bf16_f32 v72, v76, v77
	v_cvt_pk_bf16_f32 v73, v78, v79
	v_cvt_pk_bf16_f32 v74, v74, v75
	v_cvt_pk_bf16_f32 v75, v82, v83
	global_store_dwordx4 v[86:87], v[72:75], off
	global_load_dwordx4 v[72:75], v[80:81], off offset:256
	s_waitcnt vmcnt(0)
	v_lshlrev_b32_e32 v76, 16, v72
	v_and_b32_e32 v77, 0xffff0000, v72
	v_lshlrev_b32_e32 v78, 16, v73
	v_and_b32_e32 v79, 0xffff0000, v73
	v_lshlrev_b32_e32 v80, 16, v74
	v_and_b32_e32 v81, 0xffff0000, v74
	v_lshlrev_b32_e32 v82, 16, v75
	v_and_b32_e32 v83, 0xffff0000, v75
	global_load_dwordx4 v[72:75], v[86:87], off offset:256
	s_waitcnt vmcnt(0)
	v_lshlrev_b32_e32 v84, 16, v72
	v_and_b32_e32 v85, 0xffff0000, v72
	v_lshlrev_b32_e32 v72, 16, v73
	v_and_b32_e32 v73, 0xffff0000, v73
	v_lshlrev_b32_e32 v88, 16, v74
	v_and_b32_e32 v89, 0xffff0000, v74
	v_lshlrev_b32_e32 v74, 16, v75
	v_and_b32_e32 v75, 0xffff0000, v75
	v_pk_fma_f32 v[70:71], v[70:71], v[78:79], v[72:73]
	v_pk_fma_f32 v[68:69], v[68:69], v[76:77], v[84:85]
	v_pk_fma_f32 v[72:73], v[66:67], v[82:83], v[74:75]
	v_pk_fma_f32 v[66:67], v[64:65], v[80:81], v[88:89]
	v_cvt_pk_bf16_f32 v64, v68, v69
	v_cvt_pk_bf16_f32 v65, v70, v71
	v_cvt_pk_bf16_f32 v66, v66, v67
	v_cvt_pk_bf16_f32 v67, v72, v73
	global_store_dwordx4 v[86:87], v[64:67], off offset:256
	v_lshl_add_u64 v[70:71], v[140:141], 0, s[2:3]
	s_mov_b64 s[2:3], 0x48000
	v_lshl_add_u64 v[64:65], s[10:11], 0, v[70:71]
	global_load_dwordx4 v[66:69], v[64:65], off
	v_lshl_add_u64 v[70:71], s[8:9], 0, v[70:71]
	s_waitcnt vmcnt(0)
	v_lshlrev_b32_e32 v72, 16, v66
	v_and_b32_e32 v73, 0xffff0000, v66
	v_lshlrev_b32_e32 v74, 16, v67
	v_and_b32_e32 v75, 0xffff0000, v67
	v_lshlrev_b32_e32 v76, 16, v68
	v_and_b32_e32 v77, 0xffff0000, v68
	v_lshlrev_b32_e32 v78, 16, v69
	v_and_b32_e32 v79, 0xffff0000, v69
	global_load_dwordx4 v[66:69], v[70:71], off
	s_waitcnt vmcnt(0)
	v_lshlrev_b32_e32 v80, 16, v66
	v_and_b32_e32 v81, 0xffff0000, v66
	v_lshlrev_b32_e32 v66, 16, v67
	v_and_b32_e32 v67, 0xffff0000, v67
	v_lshlrev_b32_e32 v82, 16, v68
	v_and_b32_e32 v83, 0xffff0000, v68
	v_lshlrev_b32_e32 v68, 16, v69
	v_and_b32_e32 v69, 0xffff0000, v69
	v_pk_fma_f32 v[62:63], v[62:63], v[74:75], v[66:67]
	v_pk_fma_f32 v[60:61], v[60:61], v[72:73], v[80:81]
	v_pk_fma_f32 v[66:67], v[58:59], v[78:79], v[68:69]
	v_pk_fma_f32 v[58:59], v[56:57], v[76:77], v[82:83]
	v_cvt_pk_bf16_f32 v56, v60, v61
	v_cvt_pk_bf16_f32 v57, v62, v63
	v_cvt_pk_bf16_f32 v58, v58, v59
	v_cvt_pk_bf16_f32 v59, v66, v67
	global_store_dwordx4 v[70:71], v[56:59], off
	global_load_dwordx4 v[56:59], v[64:65], off offset:256
	s_waitcnt vmcnt(0)
	v_lshlrev_b32_e32 v60, 16, v56
	v_and_b32_e32 v61, 0xffff0000, v56
	v_lshlrev_b32_e32 v62, 16, v57
	v_and_b32_e32 v63, 0xffff0000, v57
	v_lshlrev_b32_e32 v64, 16, v58
	v_and_b32_e32 v65, 0xffff0000, v58
	v_lshlrev_b32_e32 v66, 16, v59
	v_and_b32_e32 v67, 0xffff0000, v59
	global_load_dwordx4 v[56:59], v[70:71], off offset:256
	s_waitcnt vmcnt(0)
	v_lshlrev_b32_e32 v68, 16, v56
	v_and_b32_e32 v69, 0xffff0000, v56
	v_lshlrev_b32_e32 v56, 16, v57
	v_and_b32_e32 v57, 0xffff0000, v57
	v_lshlrev_b32_e32 v72, 16, v58
	v_and_b32_e32 v73, 0xffff0000, v58
	v_lshlrev_b32_e32 v58, 16, v59
	v_and_b32_e32 v59, 0xffff0000, v59
	v_pk_fma_f32 v[54:55], v[54:55], v[62:63], v[56:57]
	v_pk_fma_f32 v[52:53], v[52:53], v[60:61], v[68:69]
	v_pk_fma_f32 v[56:57], v[50:51], v[66:67], v[58:59]
	v_pk_fma_f32 v[50:51], v[48:49], v[64:65], v[72:73]
	v_cvt_pk_bf16_f32 v48, v52, v53
	v_cvt_pk_bf16_f32 v49, v54, v55
	v_cvt_pk_bf16_f32 v50, v50, v51
	v_cvt_pk_bf16_f32 v51, v56, v57
	global_store_dwordx4 v[70:71], v[48:51], off offset:256
	v_lshl_add_u64 v[54:55], v[140:141], 0, s[2:3]
	s_mov_b64 s[2:3], 0x50000
	v_lshl_add_u64 v[48:49], s[10:11], 0, v[54:55]
	global_load_dwordx4 v[50:53], v[48:49], off
	v_lshl_add_u64 v[54:55], s[8:9], 0, v[54:55]
	s_waitcnt vmcnt(0)
	v_lshlrev_b32_e32 v56, 16, v50
	v_and_b32_e32 v57, 0xffff0000, v50
	v_lshlrev_b32_e32 v58, 16, v51
	v_and_b32_e32 v59, 0xffff0000, v51
	v_lshlrev_b32_e32 v60, 16, v52
	v_and_b32_e32 v61, 0xffff0000, v52
	v_lshlrev_b32_e32 v62, 16, v53
	v_and_b32_e32 v63, 0xffff0000, v53
	global_load_dwordx4 v[50:53], v[54:55], off
	s_waitcnt vmcnt(0)
	v_lshlrev_b32_e32 v64, 16, v50
	v_and_b32_e32 v65, 0xffff0000, v50
	v_lshlrev_b32_e32 v50, 16, v51
	v_and_b32_e32 v51, 0xffff0000, v51
	v_lshlrev_b32_e32 v66, 16, v52
	v_and_b32_e32 v67, 0xffff0000, v52
	v_lshlrev_b32_e32 v52, 16, v53
	v_and_b32_e32 v53, 0xffff0000, v53
	v_pk_fma_f32 v[46:47], v[46:47], v[58:59], v[50:51]
	v_pk_fma_f32 v[44:45], v[44:45], v[56:57], v[64:65]
	v_pk_fma_f32 v[50:51], v[42:43], v[62:63], v[52:53]
	v_pk_fma_f32 v[42:43], v[40:41], v[60:61], v[66:67]
	v_cvt_pk_bf16_f32 v40, v44, v45
	v_cvt_pk_bf16_f32 v41, v46, v47
	v_cvt_pk_bf16_f32 v42, v42, v43
	v_cvt_pk_bf16_f32 v43, v50, v51
	global_store_dwordx4 v[54:55], v[40:43], off
	global_load_dwordx4 v[40:43], v[48:49], off offset:256
	s_waitcnt vmcnt(0)
	v_lshlrev_b32_e32 v44, 16, v40
	v_and_b32_e32 v45, 0xffff0000, v40
	v_lshlrev_b32_e32 v46, 16, v41
	v_and_b32_e32 v47, 0xffff0000, v41
	v_lshlrev_b32_e32 v48, 16, v42
	v_and_b32_e32 v49, 0xffff0000, v42
	v_lshlrev_b32_e32 v50, 16, v43
	v_and_b32_e32 v51, 0xffff0000, v43
	global_load_dwordx4 v[40:43], v[54:55], off offset:256
	s_waitcnt vmcnt(0)
	v_lshlrev_b32_e32 v52, 16, v40
	v_and_b32_e32 v53, 0xffff0000, v40
	v_lshlrev_b32_e32 v40, 16, v41
	v_and_b32_e32 v41, 0xffff0000, v41
	v_lshlrev_b32_e32 v56, 16, v42
	v_and_b32_e32 v57, 0xffff0000, v42
	v_lshlrev_b32_e32 v42, 16, v43
	v_and_b32_e32 v43, 0xffff0000, v43
	v_pk_fma_f32 v[38:39], v[38:39], v[46:47], v[40:41]
	v_pk_fma_f32 v[36:37], v[36:37], v[44:45], v[52:53]
	v_pk_fma_f32 v[40:41], v[34:35], v[50:51], v[42:43]
	v_pk_fma_f32 v[34:35], v[32:33], v[48:49], v[56:57]
	v_cvt_pk_bf16_f32 v32, v36, v37
	v_cvt_pk_bf16_f32 v33, v38, v39
	v_cvt_pk_bf16_f32 v34, v34, v35
	v_cvt_pk_bf16_f32 v35, v40, v41
	global_store_dwordx4 v[54:55], v[32:35], off offset:256
	v_lshl_add_u64 v[38:39], v[140:141], 0, s[2:3]
	s_mov_b64 s[2:3], 0x58000
	v_lshl_add_u64 v[32:33], s[10:11], 0, v[38:39]
	global_load_dwordx4 v[34:37], v[32:33], off
	v_lshl_add_u64 v[38:39], s[8:9], 0, v[38:39]
	s_waitcnt vmcnt(0)
	v_lshlrev_b32_e32 v40, 16, v34
	v_and_b32_e32 v41, 0xffff0000, v34
	v_lshlrev_b32_e32 v42, 16, v35
	v_and_b32_e32 v43, 0xffff0000, v35
	v_lshlrev_b32_e32 v44, 16, v36
	v_and_b32_e32 v45, 0xffff0000, v36
	v_lshlrev_b32_e32 v46, 16, v37
	v_and_b32_e32 v47, 0xffff0000, v37
	global_load_dwordx4 v[34:37], v[38:39], off
	s_waitcnt vmcnt(0)
	v_lshlrev_b32_e32 v48, 16, v34
	v_and_b32_e32 v49, 0xffff0000, v34
	v_lshlrev_b32_e32 v34, 16, v35
	v_and_b32_e32 v35, 0xffff0000, v35
	v_lshlrev_b32_e32 v50, 16, v36
	v_and_b32_e32 v51, 0xffff0000, v36
	v_lshlrev_b32_e32 v36, 16, v37
	v_and_b32_e32 v37, 0xffff0000, v37
	v_pk_fma_f32 v[30:31], v[30:31], v[42:43], v[34:35]
	v_pk_fma_f32 v[28:29], v[28:29], v[40:41], v[48:49]
	v_pk_fma_f32 v[34:35], v[26:27], v[46:47], v[36:37]
	v_pk_fma_f32 v[26:27], v[24:25], v[44:45], v[50:51]
	v_cvt_pk_bf16_f32 v24, v28, v29
	v_cvt_pk_bf16_f32 v25, v30, v31
	v_cvt_pk_bf16_f32 v26, v26, v27
	v_cvt_pk_bf16_f32 v27, v34, v35
	global_store_dwordx4 v[38:39], v[24:27], off
	global_load_dwordx4 v[24:27], v[32:33], off offset:256
	s_waitcnt vmcnt(0)
	v_lshlrev_b32_e32 v28, 16, v24
	v_and_b32_e32 v29, 0xffff0000, v24
	v_lshlrev_b32_e32 v30, 16, v25
	v_and_b32_e32 v31, 0xffff0000, v25
	v_lshlrev_b32_e32 v32, 16, v26
	v_and_b32_e32 v33, 0xffff0000, v26
	v_lshlrev_b32_e32 v34, 16, v27
	v_and_b32_e32 v35, 0xffff0000, v27
	global_load_dwordx4 v[24:27], v[38:39], off offset:256
	s_waitcnt vmcnt(0)
	v_lshlrev_b32_e32 v36, 16, v24
	v_and_b32_e32 v37, 0xffff0000, v24
	v_lshlrev_b32_e32 v24, 16, v25
	v_and_b32_e32 v25, 0xffff0000, v25
	v_lshlrev_b32_e32 v40, 16, v26
	v_and_b32_e32 v41, 0xffff0000, v26
	v_lshlrev_b32_e32 v26, 16, v27
	v_and_b32_e32 v27, 0xffff0000, v27
	v_pk_fma_f32 v[22:23], v[22:23], v[30:31], v[24:25]
	v_pk_fma_f32 v[20:21], v[20:21], v[28:29], v[36:37]
	v_pk_fma_f32 v[24:25], v[18:19], v[34:35], v[26:27]
	v_pk_fma_f32 v[18:19], v[16:17], v[32:33], v[40:41]
	v_cvt_pk_bf16_f32 v16, v20, v21
	v_cvt_pk_bf16_f32 v17, v22, v23
	v_cvt_pk_bf16_f32 v18, v18, v19
	v_cvt_pk_bf16_f32 v19, v24, v25
	global_store_dwordx4 v[38:39], v[16:19], off offset:256
	v_lshl_add_u64 v[22:23], v[140:141], 0, s[2:3]
	s_mov_b64 s[2:3], -1
	v_lshl_add_u64 v[16:17], s[10:11], 0, v[22:23]
	global_load_dwordx4 v[18:21], v[16:17], off
	s_waitcnt vmcnt(0)
	v_lshlrev_b32_e32 v24, 16, v18
	v_and_b32_e32 v25, 0xffff0000, v18
	v_lshlrev_b32_e32 v26, 16, v19
	v_and_b32_e32 v27, 0xffff0000, v19
	v_lshl_add_u64 v[18:19], s[8:9], 0, v[22:23]
	v_lshlrev_b32_e32 v28, 16, v20
	v_and_b32_e32 v29, 0xffff0000, v20
	v_lshlrev_b32_e32 v30, 16, v21
	v_and_b32_e32 v31, 0xffff0000, v21
	global_load_dwordx4 v[20:23], v[18:19], off
	s_waitcnt vmcnt(0)
	v_lshlrev_b32_e32 v32, 16, v20
	v_and_b32_e32 v33, 0xffff0000, v20
	v_lshlrev_b32_e32 v20, 16, v21
	v_and_b32_e32 v21, 0xffff0000, v21
	v_lshlrev_b32_e32 v34, 16, v22
	v_and_b32_e32 v35, 0xffff0000, v22
	v_lshlrev_b32_e32 v22, 16, v23
	v_and_b32_e32 v23, 0xffff0000, v23
	v_pk_fma_f32 v[14:15], v[14:15], v[26:27], v[20:21]
	v_pk_fma_f32 v[12:13], v[12:13], v[24:25], v[32:33]
	v_pk_fma_f32 v[20:21], v[10:11], v[30:31], v[22:23]
	v_pk_fma_f32 v[10:11], v[8:9], v[28:29], v[34:35]
	v_cvt_pk_bf16_f32 v8, v12, v13
	v_cvt_pk_bf16_f32 v9, v14, v15
	v_cvt_pk_bf16_f32 v10, v10, v11
	v_cvt_pk_bf16_f32 v11, v20, v21
	global_store_dwordx4 v[18:19], v[8:11], off
	global_load_dwordx4 v[8:11], v[16:17], off offset:256
	s_waitcnt vmcnt(0)
	v_lshlrev_b32_e32 v12, 16, v8
	v_and_b32_e32 v13, 0xffff0000, v8
	v_lshlrev_b32_e32 v14, 16, v9
	v_and_b32_e32 v15, 0xffff0000, v9
	v_lshlrev_b32_e32 v16, 16, v10
	v_and_b32_e32 v17, 0xffff0000, v10
	v_lshlrev_b32_e32 v20, 16, v11
	v_and_b32_e32 v21, 0xffff0000, v11
	global_load_dwordx4 v[8:11], v[18:19], off offset:256
	s_waitcnt vmcnt(0)
	v_lshlrev_b32_e32 v22, 16, v8
	v_and_b32_e32 v23, 0xffff0000, v8
	v_lshlrev_b32_e32 v8, 16, v9
	v_and_b32_e32 v9, 0xffff0000, v9
	v_lshlrev_b32_e32 v24, 16, v10
	v_and_b32_e32 v25, 0xffff0000, v10
	v_lshlrev_b32_e32 v10, 16, v11
	v_and_b32_e32 v11, 0xffff0000, v11
	v_pk_fma_f32 v[6:7], v[6:7], v[14:15], v[8:9]
	v_pk_fma_f32 v[4:5], v[4:5], v[12:13], v[22:23]
	v_pk_fma_f32 v[8:9], v[2:3], v[20:21], v[10:11]
	v_pk_fma_f32 v[2:3], v[0:1], v[16:17], v[24:25]
	v_cvt_pk_bf16_f32 v0, v4, v5
	v_cvt_pk_bf16_f32 v1, v6, v7
	v_cvt_pk_bf16_f32 v2, v2, v3
	v_cvt_pk_bf16_f32 v3, v8, v9
	global_store_dwordx4 v[18:19], v[0:3], off offset:256
	s_cbranch_vccnz .LBB0_643
	s_andn2_b64 vcc, exec, s[0:1]
	s_cbranch_vccnz .LBB0_642
	s_barrier
	s_branch .LBB0_642

.LBB0_727:
	v_lshl_add_u32 v144, s38, 8, v146
	v_lshl_or_b32 v142, s37, 8, v148
	v_ashrrev_i32_e32 v145, 31, v144
	v_ashrrev_i32_e32 v143, 31, v142
	v_lshlrev_b64 v[140:141], 10, v[144:145]
	v_lshl_add_u64 v[140:141], v[140:141], 0, v[142:143]
	v_lshlrev_b64 v[140:141], 2, v[140:141]
	s_mov_b32 s98, s2
	s_mov_b32 s99, s3
	global_load_dwordx4 v[178:181], v140, s[98:99]
	global_load_dwordx4 v[182:185], v140, s[98:99] offset:512
	s_add_u32 s98, s2, 0x10000
	s_addc_u32 s99, s3, 0
	global_load_dwordx4 v[186:189], v140, s[98:99]
	global_load_dwordx4 v[190:193], v140, s[98:99] offset:512
	s_add_u32 s98, s2, 0x20000
	s_addc_u32 s99, s3, 0
	global_load_dwordx4 v[208:211], v140, s[98:99]
	global_load_dwordx4 v[212:215], v140, s[98:99] offset:512
	s_add_u32 s98, s2, 0x30000
	s_addc_u32 s99, s3, 0
	global_load_dwordx4 v[216:219], v140, s[98:99]
	global_load_dwordx4 v[220:223], v140, s[98:99] offset:512
	s_add_u32 s98, s2, 0x80000
	s_addc_u32 s99, s3, 0
	global_load_dwordx4 v[178:181], v140, s[98:99]
	global_load_dwordx4 v[182:185], v140, s[98:99] offset:512
	s_add_u32 s98, s2, 0x90000
	s_addc_u32 s99, s3, 0
	global_load_dwordx4 v[186:189], v140, s[98:99]
	global_load_dwordx4 v[190:193], v140, s[98:99] offset:512
	s_add_u32 s98, s2, 0xa0000
	s_addc_u32 s99, s3, 0
	global_load_dwordx4 v[208:211], v140, s[98:99]
	global_load_dwordx4 v[212:215], v140, s[98:99] offset:512
	s_add_u32 s98, s2, 0xb0000
	s_addc_u32 s99, s3, 0
	global_load_dwordx4 v[216:219], v140, s[98:99]
	global_load_dwordx4 v[220:223], v140, s[98:99] offset:512
	v_lshl_add_u64 v[158:159], s[2:3], 0, v[140:141]
	global_load_dwordx4 v[150:153], v[158:159], off offset:16
	global_load_dwordx4 v[154:157], v[158:159], off
	s_mov_b64 s[18:19], 0x80000
	s_andn2_b64 vcc, exec, s[4:5]
	s_waitcnt vmcnt(0)
	v_pk_add_f32 v[122:123], v[122:123], v[152:153]
	v_pk_add_f32 v[126:127], v[126:127], v[156:157]
	v_pk_add_f32 v[124:125], v[124:125], v[154:155]
	v_lshl_add_u64 v[154:155], s[6:7], 0, v[140:141]
	v_pk_add_f32 v[120:121], v[120:121], v[150:151]
	global_store_dwordx4 v[154:155], v[124:127], off
	global_store_dwordx4 v[154:155], v[120:123], off offset:16
	global_load_dwordx4 v[120:123], v[158:159], off offset:528
	s_nop 0
	global_load_dwordx4 v[124:127], v[158:159], off offset:512
	s_waitcnt vmcnt(1)
	v_pk_add_f32 v[114:115], v[114:115], v[122:123]
	v_pk_add_f32 v[112:113], v[112:113], v[120:121]
	global_store_dwordx4 v[154:155], v[112:115], off offset:528
	s_waitcnt vmcnt(1)
	v_pk_add_f32 v[118:119], v[118:119], v[126:127]
	v_pk_add_f32 v[116:117], v[116:117], v[124:125]
	v_or_b32_e32 v112, 16, v144
	v_ashrrev_i32_e32 v113, 31, v112
	v_lshlrev_b64 v[112:113], 10, v[112:113]
	v_lshl_add_u64 v[112:113], v[112:113], 0, v[142:143]
	global_store_dwordx4 v[154:155], v[116:119], off offset:512
	v_lshlrev_b64 v[120:121], 2, v[112:113]
	v_lshl_add_u64 v[122:123], s[2:3], 0, v[120:121]
	global_load_dwordx4 v[112:115], v[122:123], off offset:16
	global_load_dwordx4 v[116:119], v[122:123], off
	s_waitcnt vmcnt(1)
	v_pk_add_f32 v[106:107], v[106:107], v[114:115]
	s_waitcnt vmcnt(0)
	v_pk_add_f32 v[110:111], v[110:111], v[118:119]
	v_pk_add_f32 v[108:109], v[108:109], v[116:117]
	v_lshl_add_u64 v[116:117], s[6:7], 0, v[120:121]
	v_pk_add_f32 v[104:105], v[104:105], v[112:113]
	global_store_dwordx4 v[116:117], v[108:111], off
	global_store_dwordx4 v[116:117], v[104:107], off offset:16
	global_load_dwordx4 v[104:107], v[122:123], off offset:528
	s_nop 0
	global_load_dwordx4 v[108:111], v[122:123], off offset:512
	s_waitcnt vmcnt(1)
	v_pk_add_f32 v[98:99], v[98:99], v[106:107]
	v_pk_add_f32 v[96:97], v[96:97], v[104:105]
	global_store_dwordx4 v[116:117], v[96:99], off offset:528
	s_waitcnt vmcnt(1)
	v_pk_add_f32 v[102:103], v[102:103], v[110:111]
	v_pk_add_f32 v[100:101], v[100:101], v[108:109]
	v_or_b32_e32 v96, 32, v144
	v_ashrrev_i32_e32 v97, 31, v96
	v_lshlrev_b64 v[96:97], 10, v[96:97]
	v_lshl_add_u64 v[96:97], v[96:97], 0, v[142:143]
	global_store_dwordx4 v[116:117], v[100:103], off offset:512
	v_lshlrev_b64 v[104:105], 2, v[96:97]
	v_lshl_add_u64 v[106:107], s[2:3], 0, v[104:105]
	global_load_dwordx4 v[96:99], v[106:107], off offset:16
	global_load_dwordx4 v[100:103], v[106:107], off
	s_waitcnt vmcnt(1)
	v_pk_add_f32 v[90:91], v[90:91], v[98:99]
	s_waitcnt vmcnt(0)
	v_pk_add_f32 v[94:95], v[94:95], v[102:103]
	v_pk_add_f32 v[92:93], v[92:93], v[100:101]
	v_lshl_add_u64 v[100:101], s[6:7], 0, v[104:105]
	v_pk_add_f32 v[88:89], v[88:89], v[96:97]
	global_store_dwordx4 v[100:101], v[92:95], off
	global_store_dwordx4 v[100:101], v[88:91], off offset:16
	global_load_dwordx4 v[88:91], v[106:107], off offset:528
	s_nop 0
	global_load_dwordx4 v[92:95], v[106:107], off offset:512
	s_waitcnt vmcnt(1)
	v_pk_add_f32 v[82:83], v[82:83], v[90:91]
	v_pk_add_f32 v[80:81], v[80:81], v[88:89]
	global_store_dwordx4 v[100:101], v[80:83], off offset:528
	s_waitcnt vmcnt(1)
	v_pk_add_f32 v[86:87], v[86:87], v[94:95]
	v_pk_add_f32 v[84:85], v[84:85], v[92:93]
	v_or_b32_e32 v80, 48, v144
	v_ashrrev_i32_e32 v81, 31, v80
	v_lshlrev_b64 v[80:81], 10, v[80:81]
	v_lshl_add_u64 v[80:81], v[80:81], 0, v[142:143]
	global_store_dwordx4 v[100:101], v[84:87], off offset:512
	v_lshlrev_b64 v[88:89], 2, v[80:81]
	v_lshl_add_u64 v[90:91], s[2:3], 0, v[88:89]
	global_load_dwordx4 v[80:83], v[90:91], off offset:16
	global_load_dwordx4 v[84:87], v[90:91], off
	s_waitcnt vmcnt(1)
	v_pk_add_f32 v[74:75], v[74:75], v[82:83]
	s_waitcnt vmcnt(0)
	v_pk_add_f32 v[78:79], v[78:79], v[86:87]
	v_pk_add_f32 v[76:77], v[76:77], v[84:85]
	v_lshl_add_u64 v[84:85], s[6:7], 0, v[88:89]
	v_pk_add_f32 v[72:73], v[72:73], v[80:81]
	global_store_dwordx4 v[84:85], v[76:79], off
	global_store_dwordx4 v[84:85], v[72:75], off offset:16
	global_load_dwordx4 v[72:75], v[90:91], off offset:528
	s_nop 0
	global_load_dwordx4 v[76:79], v[90:91], off offset:512
	s_waitcnt vmcnt(1)
	v_pk_add_f32 v[66:67], v[66:67], v[74:75]
	s_waitcnt vmcnt(0)
	v_pk_add_f32 v[70:71], v[70:71], v[78:79]
	v_pk_add_f32 v[68:69], v[68:69], v[76:77]
	v_pk_add_f32 v[64:65], v[64:65], v[72:73]
	global_store_dwordx4 v[84:85], v[68:71], off offset:512
	global_store_dwordx4 v[84:85], v[64:67], off offset:528
	v_lshl_add_u64 v[72:73], v[140:141], 0, s[18:19]
	v_lshl_add_u64 v[74:75], s[2:3], 0, v[72:73]
	global_load_dwordx4 v[64:67], v[74:75], off offset:16
	global_load_dwordx4 v[68:71], v[74:75], off
	s_mov_b64 s[18:19], 0x90000
	s_waitcnt vmcnt(1)
	v_pk_add_f32 v[58:59], v[58:59], v[66:67]
	s_waitcnt vmcnt(0)
	v_pk_add_f32 v[62:63], v[62:63], v[70:71]
	v_pk_add_f32 v[60:61], v[60:61], v[68:69]
	v_lshl_add_u64 v[68:69], s[6:7], 0, v[72:73]
	v_pk_add_f32 v[56:57], v[56:57], v[64:65]
	global_store_dwordx4 v[68:69], v[60:63], off
	global_store_dwordx4 v[68:69], v[56:59], off offset:16
	global_load_dwordx4 v[56:59], v[74:75], off offset:528
	s_nop 0
	global_load_dwordx4 v[60:63], v[74:75], off offset:512
	s_waitcnt vmcnt(1)
	v_pk_add_f32 v[50:51], v[50:51], v[58:59]
	s_waitcnt vmcnt(0)
	v_pk_add_f32 v[54:55], v[54:55], v[62:63]
	v_pk_add_f32 v[52:53], v[52:53], v[60:61]
	v_pk_add_f32 v[48:49], v[48:49], v[56:57]
	global_store_dwordx4 v[68:69], v[52:55], off offset:512
	global_store_dwordx4 v[68:69], v[48:51], off offset:528
	v_lshl_add_u64 v[56:57], v[140:141], 0, s[18:19]
	v_lshl_add_u64 v[58:59], s[2:3], 0, v[56:57]
	global_load_dwordx4 v[48:51], v[58:59], off offset:16
	global_load_dwordx4 v[52:55], v[58:59], off
	s_mov_b64 s[18:19], 0xa0000
	s_waitcnt vmcnt(1)
	v_pk_add_f32 v[42:43], v[42:43], v[50:51]
	s_waitcnt vmcnt(0)
	v_pk_add_f32 v[46:47], v[46:47], v[54:55]
	v_pk_add_f32 v[44:45], v[44:45], v[52:53]
	v_lshl_add_u64 v[52:53], s[6:7], 0, v[56:57]
	v_pk_add_f32 v[40:41], v[40:41], v[48:49]
	global_store_dwordx4 v[52:53], v[44:47], off
	global_store_dwordx4 v[52:53], v[40:43], off offset:16
	global_load_dwordx4 v[40:43], v[58:59], off offset:528
	s_nop 0
	global_load_dwordx4 v[44:47], v[58:59], off offset:512
	s_waitcnt vmcnt(1)
	v_pk_add_f32 v[34:35], v[34:35], v[42:43]
	s_waitcnt vmcnt(0)
	v_pk_add_f32 v[38:39], v[38:39], v[46:47]
	v_pk_add_f32 v[36:37], v[36:37], v[44:45]
	v_pk_add_f32 v[32:33], v[32:33], v[40:41]
	global_store_dwordx4 v[52:53], v[36:39], off offset:512
	global_store_dwordx4 v[52:53], v[32:35], off offset:528
	v_lshl_add_u64 v[40:41], v[140:141], 0, s[18:19]
	v_lshl_add_u64 v[42:43], s[2:3], 0, v[40:41]
	global_load_dwordx4 v[32:35], v[42:43], off offset:16
	global_load_dwordx4 v[36:39], v[42:43], off
	s_mov_b64 s[18:19], 0xb0000
	s_waitcnt vmcnt(1)
	v_pk_add_f32 v[26:27], v[26:27], v[34:35]
	s_waitcnt vmcnt(0)
	v_pk_add_f32 v[30:31], v[30:31], v[38:39]
	v_pk_add_f32 v[28:29], v[28:29], v[36:37]
	v_lshl_add_u64 v[36:37], s[6:7], 0, v[40:41]
	v_pk_add_f32 v[24:25], v[24:25], v[32:33]
	global_store_dwordx4 v[36:37], v[28:31], off
	global_store_dwordx4 v[36:37], v[24:27], off offset:16
	global_load_dwordx4 v[24:27], v[42:43], off offset:528
	s_nop 0
	global_load_dwordx4 v[28:31], v[42:43], off offset:512
	s_waitcnt vmcnt(1)
	v_pk_add_f32 v[18:19], v[18:19], v[26:27]
	s_waitcnt vmcnt(0)
	v_pk_add_f32 v[22:23], v[22:23], v[30:31]
	v_pk_add_f32 v[20:21], v[20:21], v[28:29]
	v_pk_add_f32 v[16:17], v[16:17], v[24:25]
	global_store_dwordx4 v[36:37], v[20:23], off offset:512
	global_store_dwordx4 v[36:37], v[16:19], off offset:528
	v_lshl_add_u64 v[24:25], v[140:141], 0, s[18:19]
	v_lshl_add_u64 v[26:27], s[2:3], 0, v[24:25]
	global_load_dwordx4 v[16:19], v[26:27], off offset:16
	global_load_dwordx4 v[20:23], v[26:27], off
	s_mov_b64 s[18:19], -1
	s_waitcnt vmcnt(1)
	v_pk_add_f32 v[10:11], v[10:11], v[18:19]
	s_waitcnt vmcnt(0)
	v_pk_add_f32 v[14:15], v[14:15], v[22:23]
	v_pk_add_f32 v[12:13], v[12:13], v[20:21]
	v_lshl_add_u64 v[20:21], s[6:7], 0, v[24:25]
	v_pk_add_f32 v[8:9], v[8:9], v[16:17]
	global_store_dwordx4 v[20:21], v[12:15], off
	global_store_dwordx4 v[20:21], v[8:11], off offset:16
	global_load_dwordx4 v[8:11], v[26:27], off offset:528
	s_nop 0
	global_load_dwordx4 v[12:15], v[26:27], off offset:512
	s_waitcnt vmcnt(1)
	v_pk_add_f32 v[2:3], v[2:3], v[10:11]
	s_waitcnt vmcnt(0)
	v_pk_add_f32 v[6:7], v[6:7], v[14:15]
	v_pk_add_f32 v[4:5], v[4:5], v[12:13]
	v_pk_add_f32 v[0:1], v[0:1], v[8:9]
	global_store_dwordx4 v[20:21], v[4:7], off offset:512
	global_store_dwordx4 v[20:21], v[0:3], off offset:528
	s_cbranch_vccnz .LBB0_716
	s_andn2_b64 vcc, exec, s[0:1]
	s_cbranch_vccnz .LBB0_715
	s_barrier
	s_branch .LBB0_715
